# flat-release barrier with 3-deep pipelined polling of TOP (s_sleep 10 spacing)
# speedup vs baseline: 1.0063x; 1.0016x over previous
; __device__ __forceinline__ unsigned xb_ld(unsigned* p)              { return __hip_atomic_load(p, __ATOMIC_RELAXED, __HIP_MEMORY_SCOPE_AGENT); }
; __device__ __forceinline__ unsigned xb_add(unsigned* p, unsigned v) { return __hip_atomic_fetch_add(p, v, __ATOMIC_RELAXED, __HIP_MEMORY_SCOPE_AGENT); }
; #define XB_SPIN(cond, bar) do { unsigned _sp = 0; while (cond) { __builtin_amdgcn_s_sleep(1); \
;     if ((++_sp & 255u) == 0u) { if (xb_ld(&(bar)[XB_TMO])) break; if (_sp > XB_SPIN_CAP) { atomicAdd(&(bar)[XB_TMO], 1u); break; } } } } while (0)
; __device__ __forceinline__ void xcd_barrier(const XcdBarrier& b) {
;     ...
;             const unsigned og = xb_add(&bar[XB_TOP], 1u);
;             const unsigned tg = og / nx;
;             if (og + 1u == (tg + 1u) * nx) xb_add(&bar[XB_TOPGEN], 1u);
;             else XB_SPIN(xb_ld(&bar[XB_TOPGEN]) == tg, bar);
;             __builtin_amdgcn_fence(__ATOMIC_ACQUIRE, "agent");
;             xb_add(&bar[XB_XGEN(b.x)], 1u);
;             asm volatile("s_waitcnt vmcnt(0)" ::: "memory");
;         } else {
;             XB_SPIN(xb_ld(&bar[XB_XGEN(b.x)]) == gen, bar);
;             __builtin_amdgcn_fence(__ATOMIC_ACQUIRE, "agent");
.Lxb0_poll:
	s_waitcnt lgkmcnt(0)
	v_add_u32_e32 v1, 1, v1
	v_mul_lo_u32 v1, v1, v0
	v_mov_b32_e32 v2, 0x303000
	s_mov_b32 s3, 0
	global_load_dword v3, v2, s[70:71] offset:1024 sc1
	s_sleep 10
	global_load_dword v4, v2, s[70:71] offset:1024 sc1
	s_sleep 10
	global_load_dword v5, v2, s[70:71] offset:1024 sc1
.Lxb0_spin:
	s_sleep 10
	s_waitcnt vmcnt(2)
	v_cmp_ge_u32_e32 vcc, v3, v1
	s_cbranch_vccnz .Lxb0_done
	global_load_dword v3, v2, s[70:71] offset:1024 sc1
	s_sleep 10
	s_waitcnt vmcnt(2)
	v_cmp_ge_u32_e32 vcc, v4, v1
	s_cbranch_vccnz .Lxb0_done
	global_load_dword v4, v2, s[70:71] offset:1024 sc1
	s_sleep 10
	s_waitcnt vmcnt(2)
	v_cmp_ge_u32_e32 vcc, v5, v1
	s_cbranch_vccnz .Lxb0_done
	global_load_dword v5, v2, s[70:71] offset:1024 sc1
	s_add_i32 s3, s3, 1
	s_cmp_lt_u32 s3, 0x40000
	s_cbranch_scc1 .Lxb0_spin
